# w_br_a/w_br_b/w_out/w_fc1 bf16 copies moved from P0 to the workgroups idle in P2's last round
# speedup vs baseline: 1.0030x; 1.0030x over previous
.LBB0_42:
	s_or_b64 exec, exec, s[10:11]
	s_cmpk_gt_i32 s80, 0x107f
	s_cbranch_scc1 .LBB0_83
	v_and_b32_e32 v1, 31, v210
	v_readlane_b32 s4, v254, 0
	v_lshlrev_b32_e32 v2, 2, v1
	v_readlane_b32 s5, v254, 1
	v_lshlrev_b32_e32 v1, 3, v210
	v_mov_b32_e32 v3, 0
	v_and_b32_e32 v1, 56, v1
	v_readlane_b32 s4, v254, 48
	v_lshlrev_b32_e32 v28, 1, v1
	v_mov_b32_e32 v29, v3
	v_readlane_b32 s5, v254, 49
	v_readlane_b32 s36, v254, 28
	v_readlane_b32 s0, v254, 44
	v_lshl_add_u64 v[8:9], s[4:5], 0, v[28:29]
	v_readlane_b32 s4, v254, 46
	v_readlane_b32 s37, v254, 29
	v_readlane_b32 s38, v254, 30
	v_readlane_b32 s39, v254, 31
	v_readlane_b32 s40, v254, 32
	v_readlane_b32 s41, v254, 33
	v_readlane_b32 s42, v254, 34
	v_readlane_b32 s43, v254, 35
	v_readlane_b32 s44, v254, 36
	v_readlane_b32 s45, v254, 37
	v_readlane_b32 s46, v254, 38
	v_readlane_b32 s47, v254, 39
	v_readlane_b32 s48, v254, 40
	v_readlane_b32 s49, v254, 41
	v_readlane_b32 s50, v254, 42
	v_readlane_b32 s51, v254, 43
	s_lshl_b32 s0, s0, 14
	v_lshrrev_b32_e32 v35, 3, v217
	v_readlane_b32 s5, v254, 47
	v_lshl_add_u64 v[14:15], s[50:51], 0, v[2:3]
	v_lshl_add_u64 v[18:19], s[48:49], 0, v[2:3]
	v_lshl_add_u64 v[22:23], s[46:47], 0, v[2:3]
	v_lshl_add_u64 v[26:27], s[42:43], 0, v[2:3]
	v_readlane_b32 s36, v254, 12
	s_add_i32 s0, s0, 0
	v_lshrrev_b32_e32 v0, 5, v217
	v_readlane_b32 s6, v254, 2
	v_readlane_b32 s7, v254, 3
	v_readlane_b32 s8, v254, 4
	v_readlane_b32 s9, v254, 5
	v_readlane_b32 s10, v254, 6
	v_readlane_b32 s11, v254, 7
	v_mul_u32_u24_e32 v7, 0x84, v1
	v_lshlrev_b32_e32 v1, 2, v35
	v_lshl_add_u64 v[12:13], s[4:5], 0, v[28:29]
	v_lshl_add_u64 v[20:21], s[78:79], 0, v[28:29]
	s_mov_b64 s[4:5], 0xa00400
	v_readlane_b32 s42, v254, 18
	v_readlane_b32 s43, v254, 19
	s_mov_b32 s1, 0
	v_lshl_add_u64 v[4:5], s[8:9], 0, v[2:3]
	v_add_u32_e32 v6, s0, v2
	s_movk_i32 s3, 0x84
	v_add3_u32 v36, s0, v7, v1
	v_or_b32_e32 v37, 8, v35
	v_or_b32_e32 v38, 16, v35
	v_or_b32_e32 v39, 24, v35
	v_lshl_add_u64 v[10:11], s[6:7], 0, v[2:3]
	v_lshl_add_u64 v[16:17], s[92:93], 0, v[28:29]
	v_lshl_add_u64 v[20:21], v[20:21], 0, s[4:5]
	v_lshl_add_u64 v[24:25], s[88:89], 0, v[28:29]
	v_lshl_add_u64 v[28:29], s[96:97], 0, v[28:29]
	v_lshl_add_u64 v[30:31], s[42:43], 0, v[2:3]
	v_mov_b32_e32 v1, v0
	s_movk_i32 s8, 0x7fff
	s_mov_b32 s9, 0xffff0000
	s_movk_i32 s10, 0x2000
	s_movk_i32 s11, 0x4000
	s_movk_i32 s12, 0x2400
	s_movk_i32 s13, 0xff03
	v_mov_b32_e32 v40, 0x303
	v_mov_b32_e32 v41, 0xf03
	v_mov_b32_e32 v42, 0x1f03
	v_mov_b32_e32 v43, 0xffffff03
	s_mov_b32 s98, s80
	s_cmpk_lt_i32 s98, 0x880
	s_cselect_b32 s14, 0, 0xc00
	s_add_i32 s14, s14, s98
	v_readlane_b32 s37, v254, 13
	v_readlane_b32 s38, v254, 14
	v_readlane_b32 s39, v254, 15
	v_readlane_b32 s40, v254, 16
	v_readlane_b32 s41, v254, 17
	v_readlane_b32 s44, v254, 20
	v_readlane_b32 s45, v254, 21
	v_readlane_b32 s46, v254, 22
	v_readlane_b32 s47, v254, 23
	v_readlane_b32 s48, v254, 24
	v_readlane_b32 s49, v254, 25
	v_readlane_b32 s50, v254, 26
	v_readlane_b32 s51, v254, 27
	s_branch .LBB0_45
.LBB0_44:
	s_add_i32 s98, s98, s34
	s_cmpk_gt_i32 s98, 0x107f
	s_cbranch_scc1 .LBB0_83
	s_cmpk_lt_i32 s98, 0x880
	s_cselect_b32 s14, 0, 0xc00
	s_add_i32 s14, s14, s98

.LBB0_339:
	s_cmp_lt_u32 s2, 160
	s_cbranch_scc1 .Lxw_a_skip
	v_readfirstlane_b32 s37, v210
	s_sub_i32 s36, s2, 160
	s_lshl_b32 s36, s36, 3
	s_lshr_b32 s37, s37, 6
	s_add_i32 s37, s37, s36
	v_readlane_b32 s12, v254, 38
	v_readlane_b32 s13, v254, 39
	s_add_u32 s14, s78, 0xa00000
	s_addc_u32 s15, s79, 0
	v_and_b32_e32 v0, 63, v210
	v_and_b32_e32 v1, 7, v0
	v_lshrrev_b32_e32 v2, 3, v0
	v_mul_u32_u24_e32 v3, 0x8000, v2
	v_lshl_add_u32 v3, v1, 4, v3
	v_and_b32_e32 v4, 1, v1
	v_lshlrev_b32_e32 v4, 4, v4
	v_lshrrev_b32_e32 v5, 1, v1
	v_lshl_add_u32 v4, v5, 2, v4
	v_mul_u32_u24_e32 v4, 0x800, v4
	v_lshl_add_u32 v4, v2, 4, v4
	v_add_u32_e32 v5, 0x800, v4
	v_add_u32_e32 v6, 0x1000, v4
	v_add_u32_e32 v7, 0x1800, v4
	s_mov_b32 s35, s37
	s_cmp_ge_u32 s35, 256
	s_cbranch_scc1 .Lxp_bra_done
.Lxp_bra_loop:
	s_lshr_b32 s0, s35, 5
	s_and_b32 s1, s35, 31
	s_mul_i32 s3, s0, 0x40000
	s_lshl_b32 s20, s1, 7
	s_add_u32 s3, s3, s20
	s_add_u32 s8, s12, s3
	s_addc_u32 s9, s13, 0
	s_lshl_b32 s20, s1, 5
	s_and_b32 s21, s20, 0xffffff00
	s_bfe_u32 s3, s20, 0x10005
	s_lshl_b32 s3, s3, 7
	s_add_i32 s21, s21, s3
	s_bfe_u32 s3, s20, 0x20006
	s_lshl_b32 s3, s3, 5
	s_add_i32 s21, s21, s3
	s_mul_i32 s21, s21, 0x800
	s_lshl_b32 s3, s0, 7
	s_add_u32 s21, s21, s3
	s_add_u32 s10, s14, s21
	s_addc_u32 s11, s15, 0
	global_load_dwordx4 v[16:19], v3, s[8:9]
	s_add_u32 s8, s8, 0x1000
	s_addc_u32 s9, s9, 0
	global_load_dwordx4 v[20:23], v3, s[8:9]
	s_add_u32 s8, s8, 0x1000
	s_addc_u32 s9, s9, 0
	global_load_dwordx4 v[24:27], v3, s[8:9]
	s_add_u32 s8, s8, 0x1000
	s_addc_u32 s9, s9, 0
	global_load_dwordx4 v[28:31], v3, s[8:9]
	s_add_u32 s8, s8, 0x1000
	s_addc_u32 s9, s9, 0
	global_load_dwordx4 v[32:35], v3, s[8:9]
	s_add_u32 s8, s8, 0x1000
	s_addc_u32 s9, s9, 0
	global_load_dwordx4 v[36:39], v3, s[8:9]
	s_add_u32 s8, s8, 0x1000
	s_addc_u32 s9, s9, 0
	global_load_dwordx4 v[40:43], v3, s[8:9]
	s_add_u32 s8, s8, 0x1000
	s_addc_u32 s9, s9, 0
	global_load_dwordx4 v[44:47], v3, s[8:9]
	s_waitcnt vmcnt(0)
	v_cvt_pk_bf16_f32 v48, v16, v20
	v_cvt_pk_bf16_f32 v49, v24, v28
	v_cvt_pk_bf16_f32 v50, v32, v36
	v_cvt_pk_bf16_f32 v51, v40, v44
	v_cvt_pk_bf16_f32 v52, v17, v21
	v_cvt_pk_bf16_f32 v53, v25, v29
	v_cvt_pk_bf16_f32 v54, v33, v37
	v_cvt_pk_bf16_f32 v55, v41, v45
	v_cvt_pk_bf16_f32 v56, v18, v22
	v_cvt_pk_bf16_f32 v57, v26, v30
	v_cvt_pk_bf16_f32 v58, v34, v38
	v_cvt_pk_bf16_f32 v59, v42, v46
	v_cvt_pk_bf16_f32 v60, v19, v23
	v_cvt_pk_bf16_f32 v61, v27, v31
	v_cvt_pk_bf16_f32 v62, v35, v39
	v_cvt_pk_bf16_f32 v63, v43, v47
	global_store_dwordx4 v4, v[48:51], s[10:11]
	global_store_dwordx4 v5, v[52:55], s[10:11]
	global_store_dwordx4 v6, v[56:59], s[10:11]
	global_store_dwordx4 v7, v[60:63], s[10:11]
	s_add_i32 s35, s35, 768
	s_cmp_lt_u32 s35, 256
	s_cbranch_scc1 .Lxp_bra_loop
.Lxp_bra_done:
	v_readlane_b32 s12, v254, 40
	v_readlane_b32 s13, v254, 41
	s_add_u32 s14, s78, 0xa00400
	s_addc_u32 s15, s79, 0
	v_and_b32_e32 v0, 63, v210
	v_and_b32_e32 v1, 7, v0
	v_lshrrev_b32_e32 v2, 3, v0
	v_mul_u32_u24_e32 v3, 0x8000, v2
	v_lshl_add_u32 v3, v1, 4, v3
	v_and_b32_e32 v4, 1, v1
	v_lshlrev_b32_e32 v4, 4, v4
	v_lshrrev_b32_e32 v5, 1, v1
	v_lshl_add_u32 v4, v5, 2, v4
	v_mul_u32_u24_e32 v4, 0x800, v4
	v_lshl_add_u32 v4, v2, 4, v4
	v_add_u32_e32 v5, 0x800, v4
	v_add_u32_e32 v6, 0x1000, v4
	v_add_u32_e32 v7, 0x1800, v4
	s_mov_b32 s35, s37
	s_cmp_ge_u32 s35, 256
	s_cbranch_scc1 .Lxp_brb_done

.Lxp_brb_done:
	v_readlane_b32 s12, v254, 42
	v_readlane_b32 s13, v254, 43
	s_add_u32 s14, s78, 0xc00000
	s_addc_u32 s15, s79, 0
	v_and_b32_e32 v0, 63, v210
	v_and_b32_e32 v1, 7, v0
	v_lshrrev_b32_e32 v2, 3, v0
	v_mul_u32_u24_e32 v3, 0x8000, v2
	v_lshl_add_u32 v3, v1, 4, v3
	v_and_b32_e32 v4, 1, v1
	v_lshlrev_b32_e32 v4, 4, v4
	v_lshrrev_b32_e32 v5, 1, v1
	v_lshl_add_u32 v4, v5, 2, v4
	v_mul_u32_u24_e32 v4, 0x800, v4
	v_lshl_add_u32 v4, v2, 4, v4
	v_add_u32_e32 v5, 0x800, v4
	v_add_u32_e32 v6, 0x1000, v4
	v_add_u32_e32 v7, 0x1800, v4
	s_mov_b32 s35, s37
	s_cmp_ge_u32 s35, 512
	s_cbranch_scc1 .Lxp_out_done
.Lxp_out_loop:
	s_lshr_b32 s0, s35, 5
	s_and_b32 s1, s35, 31
	s_mul_i32 s3, s0, 0x40000
	s_lshl_b32 s20, s1, 7
	s_add_u32 s3, s3, s20
	s_add_u32 s8, s12, s3
	s_addc_u32 s9, s13, 0
	s_lshl_b32 s20, s1, 5
	s_and_b32 s21, s20, 0xffffff00
	s_bfe_u32 s3, s20, 0x10005
	s_lshl_b32 s3, s3, 7
	s_add_i32 s21, s21, s3
	s_bfe_u32 s3, s20, 0x20006
	s_lshl_b32 s3, s3, 5
	s_add_i32 s21, s21, s3
	s_mul_i32 s21, s21, 0x800
	s_lshl_b32 s3, s0, 7
	s_add_u32 s21, s21, s3
	s_add_u32 s10, s14, s21
	s_addc_u32 s11, s15, 0
	global_load_dwordx4 v[16:19], v3, s[8:9]
	s_add_u32 s8, s8, 0x1000
	s_addc_u32 s9, s9, 0
	global_load_dwordx4 v[20:23], v3, s[8:9]
	s_add_u32 s8, s8, 0x1000
	s_addc_u32 s9, s9, 0
	global_load_dwordx4 v[24:27], v3, s[8:9]
	s_add_u32 s8, s8, 0x1000
	s_addc_u32 s9, s9, 0
	global_load_dwordx4 v[28:31], v3, s[8:9]
	s_add_u32 s8, s8, 0x1000
	s_addc_u32 s9, s9, 0
	global_load_dwordx4 v[32:35], v3, s[8:9]
	s_add_u32 s8, s8, 0x1000
	s_addc_u32 s9, s9, 0
	global_load_dwordx4 v[36:39], v3, s[8:9]
	s_add_u32 s8, s8, 0x1000
	s_addc_u32 s9, s9, 0
	global_load_dwordx4 v[40:43], v3, s[8:9]
	s_add_u32 s8, s8, 0x1000
	s_addc_u32 s9, s9, 0
	global_load_dwordx4 v[44:47], v3, s[8:9]
	s_waitcnt vmcnt(0)
	v_cvt_pk_bf16_f32 v48, v16, v20
	v_cvt_pk_bf16_f32 v49, v24, v28
	v_cvt_pk_bf16_f32 v50, v32, v36
	v_cvt_pk_bf16_f32 v51, v40, v44
	v_cvt_pk_bf16_f32 v52, v17, v21
	v_cvt_pk_bf16_f32 v53, v25, v29
	v_cvt_pk_bf16_f32 v54, v33, v37
	v_cvt_pk_bf16_f32 v55, v41, v45
	v_cvt_pk_bf16_f32 v56, v18, v22
	v_cvt_pk_bf16_f32 v57, v26, v30
	v_cvt_pk_bf16_f32 v58, v34, v38
	v_cvt_pk_bf16_f32 v59, v42, v46
	v_cvt_pk_bf16_f32 v60, v19, v23
	v_cvt_pk_bf16_f32 v61, v27, v31
	v_cvt_pk_bf16_f32 v62, v35, v39
	v_cvt_pk_bf16_f32 v63, v43, v47
	global_store_dwordx4 v4, v[48:51], s[10:11]
	global_store_dwordx4 v5, v[52:55], s[10:11]
	global_store_dwordx4 v6, v[56:59], s[10:11]
	global_store_dwordx4 v7, v[60:63], s[10:11]
	s_add_i32 s35, s35, 768
	s_cmp_lt_u32 s35, 512
	s_cbranch_scc1 .Lxp_out_loop
.Lxp_out_done:
	v_readlane_b32 s12, v254, 2
	v_readlane_b32 s13, v254, 3
	s_add_u32 s14, s78, 0xe00000
	s_addc_u32 s15, s79, 0
	v_and_b32_e32 v0, 63, v210
	v_and_b32_e32 v1, 7, v0
	v_lshrrev_b32_e32 v2, 3, v0
	v_mul_u32_u24_e32 v3, 0x20000, v2
	v_lshl_add_u32 v3, v1, 4, v3
	v_and_b32_e32 v4, 1, v1
	v_lshlrev_b32_e32 v4, 4, v4
	v_lshrrev_b32_e32 v5, 1, v1
	v_lshl_add_u32 v4, v5, 2, v4
	v_mul_u32_u24_e32 v4, 0x800, v4
	v_lshl_add_u32 v4, v2, 4, v4
	v_add_u32_e32 v5, 0x800, v4
	v_add_u32_e32 v6, 0x1000, v4
	v_add_u32_e32 v7, 0x1800, v4
	s_mov_b32 s35, s37
	s_cmp_ge_u32 s35, 2048
	s_cbranch_scc1 .Lxp_fc1_done
.Lxp_fc1_loop:
	s_lshr_b32 s0, s35, 7
	s_and_b32 s1, s35, 127
	s_mul_i32 s3, s0, 0x100000
	s_lshl_b32 s20, s1, 7
	s_add_u32 s3, s3, s20
	s_add_u32 s8, s12, s3
	s_addc_u32 s9, s13, 0
	s_lshl_b32 s20, s1, 5
	s_and_b32 s21, s20, 0xffffff00
	s_bfe_u32 s3, s20, 0x10005
	s_lshl_b32 s3, s3, 7
	s_add_i32 s21, s21, s3
	s_bfe_u32 s3, s20, 0x20006
	s_lshl_b32 s3, s3, 5
	s_add_i32 s21, s21, s3
	s_mul_i32 s21, s21, 0x800
	s_lshl_b32 s3, s0, 7
	s_add_u32 s21, s21, s3
	s_add_u32 s10, s14, s21
	s_addc_u32 s11, s15, 0
	global_load_dwordx4 v[16:19], v3, s[8:9]
	s_add_u32 s8, s8, 0x4000
	s_addc_u32 s9, s9, 0
	global_load_dwordx4 v[20:23], v3, s[8:9]
	s_add_u32 s8, s8, 0x4000
	s_addc_u32 s9, s9, 0
	global_load_dwordx4 v[24:27], v3, s[8:9]
	s_add_u32 s8, s8, 0x4000
	s_addc_u32 s9, s9, 0
	global_load_dwordx4 v[28:31], v3, s[8:9]
	s_add_u32 s8, s8, 0x4000
	s_addc_u32 s9, s9, 0
	global_load_dwordx4 v[32:35], v3, s[8:9]
	s_add_u32 s8, s8, 0x4000
	s_addc_u32 s9, s9, 0
	global_load_dwordx4 v[36:39], v3, s[8:9]
	s_add_u32 s8, s8, 0x4000
	s_addc_u32 s9, s9, 0
	global_load_dwordx4 v[40:43], v3, s[8:9]
	s_add_u32 s8, s8, 0x4000
	s_addc_u32 s9, s9, 0
	global_load_dwordx4 v[44:47], v3, s[8:9]
	s_waitcnt vmcnt(0)
	v_cvt_pk_bf16_f32 v48, v16, v20
	v_cvt_pk_bf16_f32 v49, v24, v28
	v_cvt_pk_bf16_f32 v50, v32, v36
	v_cvt_pk_bf16_f32 v51, v40, v44
	v_cvt_pk_bf16_f32 v52, v17, v21
	v_cvt_pk_bf16_f32 v53, v25, v29
	v_cvt_pk_bf16_f32 v54, v33, v37
	v_cvt_pk_bf16_f32 v55, v41, v45
	v_cvt_pk_bf16_f32 v56, v18, v22
	v_cvt_pk_bf16_f32 v57, v26, v30
	v_cvt_pk_bf16_f32 v58, v34, v38
	v_cvt_pk_bf16_f32 v59, v42, v46
	v_cvt_pk_bf16_f32 v60, v19, v23
	v_cvt_pk_bf16_f32 v61, v27, v31
	v_cvt_pk_bf16_f32 v62, v35, v39
	v_cvt_pk_bf16_f32 v63, v43, v47
	global_store_dwordx4 v4, v[48:51], s[10:11]
	global_store_dwordx4 v5, v[52:55], s[10:11]
	global_store_dwordx4 v6, v[56:59], s[10:11]
	global_store_dwordx4 v7, v[60:63], s[10:11]
	s_add_i32 s35, s35, 768
	s_cmp_lt_u32 s35, 2048
	s_cbranch_scc1 .Lxp_fc1_loop
.Lxp_fc1_done:
.Lxw_a_skip:
	s_cmp_gt_i32 s83, 3
	s_cselect_b64 s[0:1], -1, 0
	s_and_b64 s[4:5], s[28:29], s[0:1]
	s_andn2_b64 vcc, exec, s[4:5]
	s_cbranch_vccnz .LBB0_389
	s_waitcnt vmcnt(0)
	v_cmp_eq_u32_e32 vcc, 0, v210
	s_waitcnt vmcnt(0)
	s_barrier
	s_and_saveexec_b64 s[4:5], vcc
	s_cbranch_execz .LBB0_388
	s_add_i32 s3, 0, 0x20200
	v_mov_b32_e32 v0, s3
	s_waitcnt vmcnt(0) expcnt(0) lgkmcnt(0)
	ds_read_b32 v2, v0
	s_add_i32 s3, 0, 0x20204
	v_mov_b32_e32 v0, s3
	ds_read_b32 v0, v0
	s_waitcnt lgkmcnt(1)
	v_cmp_ne_u32_e32 vcc, 0, v2
	s_cbranch_vccnz .LBB0_356
	v_readlane_b32 s6, v254, 8
	v_readlane_b32 s7, v254, 9
	s_load_dwordx2 s[10:11], s[6:7], 0x4
	s_add_u32 s6, s78, 0x1e00200
	s_addc_u32 s7, s79, 0
	s_add_u32 s8, s78, 0x1e00400
	s_addc_u32 s9, s79, 0
	s_waitcnt lgkmcnt(0)
	s_mul_i32 s3, s10, s33
	s_add_u32 s10, s78, 0x1e00500
	s_mul_i32 s3, s3, s11
	s_addc_u32 s11, s79, 0
	s_add_u32 s12, s78, 0x1e00600
	s_addc_u32 s13, s79, 0
	s_add_u32 s14, s78, 0x1e00700
	s_addc_u32 s15, s79, 0
	s_add_u32 s20, s78, 0x1e00800
	s_addc_u32 s21, s79, 0
	s_add_u32 s28, s78, 0x1e00900
	s_addc_u32 s29, s79, 0
	s_add_u32 s30, s78, 0x1e00a00
	s_addc_u32 s31, s79, 0
	s_add_u32 s42, s78, 0x1e00b00
	s_addc_u32 s43, s79, 0
	s_add_u32 s44, s78, 0x1e00c00
	s_addc_u32 s45, s79, 0
	s_add_u32 s46, s78, 0x1e00d00
	s_addc_u32 s47, s79, 0
	s_add_u32 s48, s78, 0x1e00e00
	s_addc_u32 s49, s79, 0
	s_add_u32 s50, s78, 0x1e00f00
	s_addc_u32 s51, s79, 0
	s_add_u32 s52, s78, 0x1e01000
	s_addc_u32 s53, s79, 0
	s_add_u32 s54, s78, 0x1e01100
	s_addc_u32 s55, s79, 0
	s_add_u32 s56, s78, 0x1e01200
	s_addc_u32 s57, s79, 0
	s_add_u32 s58, s78, 0x1e01300
	s_addc_u32 s59, s79, 0
	s_mov_b32 s35, 1
	v_mov_b32_e32 v16, 0
	s_branch .LBB0_344
